# retention scan: XOR swizzle of the K image in LDS (16-byte chunk index ^ row bit 3) to remove the 2-way bank conflict of the score waves' ds_read_b128; writer and both readers updated; on top of norm-
# baseline (speedup 1.0000x reference)
; #define LAS __attribute__((address_space(3)))
; template <bool GLA>
; __device__ __forceinline__ void scan_item2(LAS unsigned char* lds, const bf16* Qd, const bf16* Kd, const bf16* V, bf16* O, const float* EG, int ldqk, int ldv, int b, int h, int dvs, float e_const, int tid) {
;     const int lane = tid & 63, w = __builtin_amdgcn_readfirstlane(tid >> 6), fr = lane & 15, fq = lane >> 4, q4 = fr >> 2, p4 = fr & 3;
;     if (w >= 4) {
;         const int t2 = tid - 256, cw = w - 4;
;         const bf16* qg = Qd + (size_t)(b * SEQ + (t2 >> 5)) * ldqk + h * 256 + (t2 & 31) * 8;
;         const bf16* kg = Kd + (size_t)(b * SEQ + (t2 >> 5)) * ldqk + h * 256 + (t2 & 31) * 8;
;         const bf16* vg = V + (size_t)(b * SEQ + (t2 >> 4)) * ldv + h * 512 + dvs * 128 + (t2 & 15) * 8;
;         const float* eg = GLA ? EG + (size_t)(b * 32) * 1024 + h * 256 + (t2 & 63) * 4 : nullptr;
;         LAS unsigned char* qw = lds + SC_QI + (t2 >> 5) * SC_QS + (t2 & 31) * 16;
;         LAS unsigned char* kw = lds + SC_KI + (t2 >> 5) * SC_KS + (t2 & 31) * 16;
;         LAS unsigned char* vw = lds + SC_VI + (t2 >> 4) * SC_VS + (t2 & 15) * 16;
.LBB0_408:
	s_cmp_lt_i32 s56, 4
	s_cselect_b64 s[6:7], -1, 0
	s_cmp_gt_i32 s57, 3
	s_cselect_b64 s[8:9], -1, 0
	s_and_b64 s[6:7], s[6:7], s[8:9]
	s_andn2_b64 vcc, exec, s[6:7]
	s_cbranch_vccnz .LBB0_492
	v_mov_b32_e32 v209, v0
	s_cmpk_gt_i32 s2, 0xff
	s_cbranch_scc1 .LBB0_420
	v_bfe_u32 v3, v209, 4, 2
	v_bfe_u32 v2, v209, 2, 2
	v_lshlrev_b32_e32 v211, 3, v3
	v_or_b32_e32 v2, v211, v2
	v_lshlrev_b32_e32 v6, 3, v209
	v_mul_u32_u24_e32 v4, 0x220, v2
	v_and_b32_e32 v224, 24, v6
	s_add_i32 s1, 0, 0x10c00
	s_add_i32 s3, 0, 0x15400
	v_add3_u32 v225, 0, v4, v224
	v_and_b32_e32 v246, 16, v209
	v_xor_b32_e32 v225, v225, v246
	s_movk_i32 s6, 0x120
	v_mov_b32_e32 v4, s1
	v_mad_u32_u24 v226, v2, s6, v4
	s_add_u32 s66, s48, 0x29f00000
	v_add_u32_e32 v4, 0xffffff00, v209
	s_movk_i32 s0, 0x220
	s_addc_u32 s67, s49, 0
	v_ashrrev_i32_e32 v227, 5, v4
	v_and_b32_e32 v10, 31, v209
	s_add_u32 s68, s48, 0x25f00000
	v_lshlrev_b32_e32 v2, 3, v10
	v_ashrrev_i32_e32 v228, 4, v4
	v_lshlrev_b32_e32 v208, 4, v10
	v_mul_lo_u32 v10, v227, s0
	v_and_b32_e32 v1, 15, v209
	v_lshlrev_b32_e32 v6, 4, v3
	s_addc_u32 s69, s49, 0
	v_add_u32_e32 v229, 0, v10
	v_mul_lo_u32 v10, v228, s6
	v_lshlrev_b32_e32 v11, 4, v227
	v_add_u32_e32 v5, 0, v211
	v_add_u32_e32 v7, s3, v6
	v_mul_u32_u24_e32 v8, 0x210, v1
	v_mul_u32_u24_e32 v9, 0xa0, v1
	s_add_u32 s70, s48, 0x21f00000
	v_mov_b32_e32 v207, 0
	v_lshlrev_b32_e32 v4, 3, v1
	v_lshlrev_b32_e32 v210, 4, v1
	v_sub_u32_e32 v11, v229, v11
	v_add_u32_e32 v10, s1, v10
	v_or_b32_e32 v230, 0xffffffc0, v1
	v_add_u32_e32 v231, 0, v6
	v_lshlrev_b32_e32 v232, 2, v3
	v_mul_u32_u24_e32 v3, 0x220, v1
	v_lshl_or_b32 v206, v1, 13, v211
	s_mov_b32 s61, 0
	s_addc_u32 s71, s49, 0
	v_or_b32_e32 v233, 16, v232
	v_or_b32_e32 v242, 32, v232
	v_or_b32_e32 v243, 48, v232
	v_lshl_add_u64 v[212:213], s[48:49], 0, v[206:207]
	s_mov_b32 s42, 0xc2fc0000
	v_add_u32_e32 v248, v5, v8
	v_add_u32_e32 v249, v7, v9
	v_lshlrev_b32_e32 v206, 1, v2
	s_mov_b32 s43, 0x8000
	s_mov_b32 s44, 0x10000
	s_mov_b32 s45, 0x18000
	s_mov_b32 s46, 0x20000
	s_mov_b32 s47, 0x28000
	s_mov_b32 s52, 0x30000
	s_mov_b32 s53, 0x38000
	v_lshlrev_b32_e32 v214, 1, v4
	s_mov_b32 s54, 0x25f58000
	s_mov_b32 s55, 0x21f60000
	s_mov_b32 s62, 0x25f60000
	s_mov_b32 s63, 0x21f68000
	s_mov_b32 s74, 0x25f68000
	s_mov_b32 s75, 0x21f70000
	s_mov_b32 s76, 0x25f70000
	s_mov_b32 s77, 0x21f78000
	s_mov_b32 s78, 0x25f78000
	s_mov_b32 s79, 0x29f80000
	s_mov_b32 s80, 0x29fa0000
	s_mov_b32 s81, 0x29fc0000
	s_mov_b32 s82, 0x29fe0000
	s_mov_b64 s[72:73], 0x40000
	v_mov_b32_e32 v250, 0x42800000
	v_mov_b32_e32 v216, 0x3f317218
	v_mov_b32_e32 v251, 0x7fc00000
	v_mov_b32_e32 v252, 0xff800000
	v_add_u32_e32 v253, v11, v208
	v_add_u32_e32 v254, v10, v210
	v_add_u32_e32 v1, v231, v3
	v_and_b32_e32 v246, 8, v209
	v_lshlrev_b32_e32 v246, 1, v246
	v_xor_b32_e32 v1, v1, v246
	s_mov_b32 s83, s2
	s_branch .LBB0_412

; #define LAS __attribute__((address_space(3)))
; #define SC_BAR() do { asm volatile("s_waitcnt lgkmcnt(0)" ::: "memory"); __builtin_amdgcn_s_barrier(); asm volatile("" ::: "memory"); } while (0)
; #define LD_S(buf, ks) do { fbq[buf] = *(const LAS bf16x8s*)(lds + SC_QI + (16 * cw + fr) * SC_QS + (32 * (ks) + 8 * fq) * 2); \
;                 _Pragma("unroll") for (int tj = 0; tj < 4; ++tj) fak[buf][tj] = *(const LAS bf16x8s*)(lds + SC_KI + (16 * tj + fr) * SC_KS + (32 * (ks) + 8 * fq) * 2); } while (0)
; template <bool GLA>
; __device__ __forceinline__ void scan_item2(LAS unsigned char* lds, const bf16* Qd, const bf16* Kd, const bf16* V, bf16* O, const float* EG, int ldqk, int ldv, int b, int h, int dvs, float e_const, int tid) {
;     ...
;         for (int c = 0; c < SEQ / 64; ++c) {
; #pragma unroll
;             for (int k = 0; k < 8; ++k) { *(LAS v4u*)(qw + 8 * k * SC_QS) = qr[k]; *(LAS v4u*)(kw + 8 * k * SC_KS) = kr[k]; }
; #pragma unroll
;             for (int k = 0; k < 4; ++k) *(LAS v4u*)(vw + 16 * k * SC_VS) = vr[k];
;             if (GLA && t2 < 64) *(LAS f32x4*)(lds + SC_EI + t2 * 16) = er;
;             SC_BAR();
;             if (c + 1 < SEQ / 64) { const size_t adv = (size_t)(c + 1) * 64;
; #pragma unroll
;                 for (int k = 0; k < 8; ++k) { qr[k] = *(const v4u*)(qg + (adv + 8 * k) * ldqk); kr[k] = *(const v4u*)(kg + (adv + 8 * k) * ldqk); }
; #pragma unroll
;                 for (int k = 0; k < 4; ++k) vr[k] = *(const v4u*)(vg + (adv + 16 * k) * ldv);
;                 if (GLA && t2 < 64) er = *(const f32x4*)(eg + (size_t)(c + 1) * 1024); }
;             f32x4 sa[4];
; #pragma unroll
;             for (int tj = 0; tj < 4; ++tj) sa[tj] = (f32x4){0.f, 0.f, 0.f, 0.f};
;             bf16x8s fbq[3], fak[3][4];
;     ...
;             LD_S(0, 0); LD_S(1, 1); LD_S(2, 2);
.LBB0_418:
	v_add_u32_e32 v91, v229, v208
	v_xor_b32_e32 v246, 16, v91
	s_waitcnt vmcnt(0)
	ds_write_b128 v253, v[2:5]
	ds_write_b128 v91, v[6:9] offset:33792
	ds_write_b128 v253, v[10:13] offset:4224
	ds_write_b128 v246, v[14:17] offset:38144
	ds_write_b128 v253, v[18:21] offset:8448
	ds_write_b128 v91, v[22:25] offset:42496
	ds_write_b128 v253, v[26:29] offset:12672
	ds_write_b128 v246, v[30:33] offset:46848
	ds_write_b128 v253, v[34:37] offset:16896
	ds_write_b128 v91, v[38:41] offset:51200
	ds_write_b128 v253, v[42:45] offset:21120
	ds_write_b128 v246, v[46:49] offset:55552
	ds_write_b128 v253, v[50:53] offset:25344
	ds_write_b128 v91, v[54:57] offset:59904
	ds_write_b128 v253, v[58:61] offset:29568
	ds_write_b128 v246, v[62:65] offset:64256
	ds_write_b128 v254, v[66:69]
	ds_write_b128 v254, v[70:73] offset:4608
	ds_write_b128 v254, v[74:77] offset:9216
	ds_write_b128 v254, v[78:81] offset:13824
	v_lshl_add_u64 v[58:59], s[48:49], 0, v[82:83]
	s_mov_b32 s0, 0x21f40000
	v_add_co_u32_e64 v2, s[38:39], s0, v58
	s_mov_b32 s0, 0x25f40000
	s_nop 0
	v_addc_co_u32_e64 v3, s[38:39], 0, v59, s[38:39]
	v_add_co_u32_e64 v6, s[38:39], s0, v58
	s_mov_b32 s0, 0x21f48000
	s_nop 0
	v_addc_co_u32_e64 v7, s[38:39], 0, v59, s[38:39]
	v_add_co_u32_e64 v10, s[38:39], s0, v58
	s_mov_b32 s0, 0x25f48000
	s_nop 0
	v_addc_co_u32_e64 v11, s[38:39], 0, v59, s[38:39]
	v_add_co_u32_e64 v14, s[38:39], s0, v58
	s_mov_b32 s0, 0x21f50000
	s_nop 0
	v_addc_co_u32_e64 v15, s[38:39], 0, v59, s[38:39]
	v_add_co_u32_e64 v18, s[38:39], s0, v58
	s_mov_b32 s0, 0x25f50000
	s_nop 0
	v_addc_co_u32_e64 v19, s[38:39], 0, v59, s[38:39]
	v_add_co_u32_e64 v22, s[38:39], s0, v58
	s_mov_b32 s0, 0x21f58000
	s_nop 0
	v_addc_co_u32_e64 v23, s[38:39], 0, v59, s[38:39]
	v_add_co_u32_e64 v26, s[38:39], s0, v58
	v_lshl_add_u64 v[74:75], s[48:49], 0, v[84:85]
	s_nop 0
	v_addc_co_u32_e64 v27, s[38:39], 0, v59, s[38:39]
	v_add_co_u32_e64 v30, s[38:39], s54, v58
	s_waitcnt lgkmcnt(0)
	s_barrier
	s_nop 0
	v_addc_co_u32_e64 v31, s[38:39], 0, v59, s[38:39]
	v_add_co_u32_e64 v34, s[38:39], s55, v58
	global_load_dwordx4 v[2:5], v[2:3], off
	s_nop 0
	global_load_dwordx4 v[6:9], v[6:7], off
	v_addc_co_u32_e64 v35, s[38:39], 0, v59, s[38:39]
	v_add_co_u32_e64 v38, s[38:39], s62, v58
	global_load_dwordx4 v[10:13], v[10:11], off
	s_nop 0
	global_load_dwordx4 v[14:17], v[14:15], off
	v_addc_co_u32_e64 v39, s[38:39], 0, v59, s[38:39]
	v_add_co_u32_e64 v42, s[38:39], s63, v58
	global_load_dwordx4 v[18:21], v[18:19], off
	s_nop 0
	global_load_dwordx4 v[22:25], v[22:23], off
	v_addc_co_u32_e64 v43, s[38:39], 0, v59, s[38:39]
	v_add_co_u32_e64 v46, s[38:39], s74, v58
	global_load_dwordx4 v[26:29], v[26:27], off
	s_nop 0
	global_load_dwordx4 v[30:33], v[30:31], off
	v_addc_co_u32_e64 v47, s[38:39], 0, v59, s[38:39]
	v_add_co_u32_e64 v50, s[38:39], s75, v58
	global_load_dwordx4 v[34:37], v[34:35], off
	s_nop 0
	global_load_dwordx4 v[38:41], v[38:39], off
	v_addc_co_u32_e64 v51, s[38:39], 0, v59, s[38:39]
	v_add_co_u32_e64 v54, s[38:39], s76, v58
	global_load_dwordx4 v[42:45], v[42:43], off
	s_nop 0
	global_load_dwordx4 v[46:49], v[46:47], off
	v_addc_co_u32_e64 v55, s[38:39], 0, v59, s[38:39]
	v_add_co_u32_e64 v60, s[38:39], s77, v58
	global_load_dwordx4 v[50:53], v[50:51], off
	s_nop 0
	global_load_dwordx4 v[54:57], v[54:55], off
	v_addc_co_u32_e64 v61, s[38:39], 0, v59, s[38:39]
	v_add_co_u32_e64 v62, s[38:39], s78, v58
	s_nop 1
	v_addc_co_u32_e64 v63, s[38:39], 0, v59, s[38:39]
	v_add_co_u32_e64 v66, s[38:39], s79, v74
	global_load_dwordx4 v[58:61], v[60:61], off
	s_nop 0
	global_load_dwordx4 v[62:65], v[62:63], off
	v_addc_co_u32_e64 v67, s[38:39], 0, v75, s[38:39]
	v_add_co_u32_e64 v70, s[38:39], s80, v74
	s_nop 1
	v_addc_co_u32_e64 v71, s[38:39], 0, v75, s[38:39]
	v_add_co_u32_e64 v76, s[38:39], s81, v74
	global_load_dwordx4 v[66:69], v[66:67], off
	s_nop 0
	global_load_dwordx4 v[70:73], v[70:71], off
	v_addc_co_u32_e64 v77, s[38:39], 0, v75, s[38:39]
	v_add_co_u32_e64 v78, s[38:39], s82, v74
	s_nop 1
	v_addc_co_u32_e64 v79, s[38:39], 0, v75, s[38:39]
	global_load_dwordx4 v[74:77], v[76:77], off
	s_nop 0
	global_load_dwordx4 v[78:81], v[78:79], off
	ds_read_b128 v[92:95], v89
	ds_read_b128 v[96:99], v89 offset:64
	ds_read_b128 v[100:103], v1 offset:42496
	ds_read_b128 v[104:107], v1 offset:42560
	ds_read_b128 v[108:111], v1 offset:59904
	ds_read_b128 v[112:115], v1 offset:59968
	ds_read_b128 v[116:119], v1 offset:33792
	ds_read_b128 v[120:123], v89 offset:128
	ds_read_b128 v[124:127], v1 offset:33856
	ds_read_b128 v[128:131], v1 offset:33920
	ds_read_b128 v[132:135], v1 offset:51200
	ds_read_b128 v[136:139], v1 offset:42624
	ds_read_b128 v[140:143], v1 offset:51264
	ds_read_b128 v[144:147], v1 offset:51328
	ds_read_b128 v[148:151], v1 offset:60032
	s_waitcnt lgkmcnt(8)
	v_mfma_f32_16x16x32_bf16 v[116:119], v[116:119], v[92:95], 0
	v_mfma_f32_16x16x32_bf16 v[100:103], v[100:103], v[92:95], 0
	s_waitcnt lgkmcnt(4)
	v_mfma_f32_16x16x32_bf16 v[132:135], v[132:135], v[92:95], 0
	v_mfma_f32_16x16x32_bf16 v[92:95], v[108:111], v[92:95], 0
	ds_read_b128 v[108:111], v89 offset:192
	ds_read_b128 v[152:155], v1 offset:33984
	ds_read_b128 v[156:159], v1 offset:42688
	ds_read_b128 v[160:163], v1 offset:51392
	ds_read_b128 v[164:167], v1 offset:60096
	v_mfma_f32_16x16x32_bf16 v[92:95], v[112:115], v[96:99], v[92:95]
	v_mfma_f32_16x16x32_bf16 v[116:119], v[124:127], v[96:99], v[116:119]
	v_mfma_f32_16x16x32_bf16 v[100:103], v[104:107], v[96:99], v[100:103]
	s_waitcnt lgkmcnt(7)
; #define LAS __attribute__((address_space(3)))
; __device__ __forceinline__ unsigned cvt2(float a, float b) { f32x2s v = {a, b}; bf16x2_t r = __builtin_convertvector(v, bf16x2_t); return __builtin_bit_cast(unsigned, r); }
; #define SC_BAR() do { asm volatile("s_waitcnt lgkmcnt(0)" ::: "memory"); __builtin_amdgcn_s_barrier(); asm volatile("" ::: "memory"); } while (0)
; #define LD_S(buf, ks) do { fbq[buf] = *(const LAS bf16x8s*)(lds + SC_QI + (16 * cw + fr) * SC_QS + (32 * (ks) + 8 * fq) * 2); \
;                 _Pragma("unroll") for (int tj = 0; tj < 4; ++tj) fak[buf][tj] = *(const LAS bf16x8s*)(lds + SC_KI + (16 * tj + fr) * SC_KS + (32 * (ks) + 8 * fq) * 2); } while (0)
; template <bool GLA>
; __device__ __forceinline__ void scan_item2(LAS unsigned char* lds, const bf16* Qd, const bf16* Kd, const bf16* V, bf16* O, const float* EG, int ldqk, int ldv, int b, int h, int dvs, float e_const, int tid) {
;     ...
;         for (int c = 0; c < SEQ / 64; ++c) {
; #pragma unroll
;             for (int k = 0; k < 8; ++k) { *(LAS v4u*)(qw + 8 * k * SC_QS) = qr[k]; *(LAS v4u*)(kw + 8 * k * SC_KS) = kr[k]; }
; #pragma unroll
;             for (int k = 0; k < 4; ++k) *(LAS v4u*)(vw + 16 * k * SC_VS) = vr[k];
;             if (GLA && t2 < 64) *(LAS f32x4*)(lds + SC_EI + t2 * 16) = er;
;             SC_BAR();
;     ...
;             for (int ks = 0; ks < 8; ++ks) {
;                 __builtin_amdgcn_sched_barrier(0);
; #pragma unroll
;                 for (int tj = 0; tj < 4; ++tj) sa[tj] = __builtin_amdgcn_mfma_f32_16x16x32_bf16(fak[ks % 3][tj], fbq[ks % 3], sa[tj], 0, 0, 0);
;                 __builtin_amdgcn_sched_barrier(0);
;                 if (ks + 3 < 8) LD_S(ks % 3, ks + 3);
;             }
;     ...
;             { const int i = 16 * cw + fr;
; #pragma unroll
;               for (int tj = 0; tj < 4; ++tj) { const int j0 = 16 * tj + 4 * fq;
;                   const float p0 = (j0 + 0 <= i) ? sa[tj][0] : 0.f, p1 = (j0 + 1 <= i) ? sa[tj][1] : 0.f, p2 = (j0 + 2 <= i) ? sa[tj][2] : 0.f, p3 = (j0 + 3 <= i) ? sa[tj][3] : 0.f;
;                   v2u pw; pw.x = cvt2(p0, p1); pw.y = cvt2(p2, p3);
;                   *(LAS v2u*)(lds + SC_PI + i * SC_PS + j0 * 2) = pw; } }
;             SC_BAR();
	v_mfma_f32_16x16x32_bf16 v[104:107], v[140:143], v[96:99], v[132:135]
	ds_read_b128 v[96:99], v89 offset:256
	ds_read_b128 v[112:115], v1 offset:34048
	ds_read_b128 v[124:127], v1 offset:42752
	ds_read_b128 v[132:135], v1 offset:51456
	ds_read_b128 v[140:143], v1 offset:60160
	s_waitcnt lgkmcnt(10)
	v_mfma_f32_16x16x32_bf16 v[92:95], v[148:151], v[120:123], v[92:95]
	v_mfma_f32_16x16x32_bf16 v[116:119], v[128:131], v[120:123], v[116:119]
	v_mfma_f32_16x16x32_bf16 v[100:103], v[136:139], v[120:123], v[100:103]
	v_mfma_f32_16x16x32_bf16 v[104:107], v[144:147], v[120:123], v[104:107]
	ds_read_b128 v[120:123], v89 offset:320
	ds_read_b128 v[128:131], v1 offset:34112
	ds_read_b128 v[136:139], v1 offset:42816
	ds_read_b128 v[144:147], v1 offset:51520
	ds_read_b128 v[148:151], v1 offset:60224
	s_waitcnt lgkmcnt(10)
	v_mfma_f32_16x16x32_bf16 v[92:95], v[164:167], v[108:111], v[92:95]
	v_mfma_f32_16x16x32_bf16 v[116:119], v[152:155], v[108:111], v[116:119]
	v_mfma_f32_16x16x32_bf16 v[100:103], v[156:159], v[108:111], v[100:103]
	v_mfma_f32_16x16x32_bf16 v[104:107], v[160:163], v[108:111], v[104:107]
	ds_read_b128 v[108:111], v89 offset:384
	ds_read_b128 v[152:155], v1 offset:34176
	ds_read_b128 v[156:159], v1 offset:42880
	ds_read_b128 v[160:163], v1 offset:51584
	ds_read_b128 v[164:167], v1 offset:60288
	s_waitcnt lgkmcnt(10)
	v_mfma_f32_16x16x32_bf16 v[92:95], v[140:143], v[96:99], v[92:95]
	v_mfma_f32_16x16x32_bf16 v[112:115], v[112:115], v[96:99], v[116:119]
	v_mfma_f32_16x16x32_bf16 v[100:103], v[124:127], v[96:99], v[100:103]
	v_mfma_f32_16x16x32_bf16 v[104:107], v[132:135], v[96:99], v[104:107]
	ds_read_b128 v[96:99], v89 offset:448
	ds_read_b128 v[116:119], v1 offset:34240
	ds_read_b128 v[124:127], v1 offset:42944
	ds_read_b128 v[132:135], v1 offset:51648
	ds_read_b128 v[140:143], v1 offset:60352
	s_waitcnt lgkmcnt(10)
	v_mfma_f32_16x16x32_bf16 v[92:95], v[148:151], v[120:123], v[92:95]
	v_mfma_f32_16x16x32_bf16 v[112:115], v[128:131], v[120:123], v[112:115]
	v_mfma_f32_16x16x32_bf16 v[100:103], v[136:139], v[120:123], v[100:103]
	v_mfma_f32_16x16x32_bf16 v[104:107], v[144:147], v[120:123], v[104:107]
	s_waitcnt lgkmcnt(5)
	v_mfma_f32_16x16x32_bf16 v[92:95], v[164:167], v[108:111], v[92:95]
	v_mfma_f32_16x16x32_bf16 v[112:115], v[152:155], v[108:111], v[112:115]
	v_mfma_f32_16x16x32_bf16 v[100:103], v[156:159], v[108:111], v[100:103]
	v_mfma_f32_16x16x32_bf16 v[104:107], v[160:163], v[108:111], v[104:107]
	s_waitcnt lgkmcnt(3)
	v_mfma_f32_16x16x32_bf16 v[108:111], v[116:119], v[96:99], v[112:115]
	s_waitcnt lgkmcnt(2)
	v_mfma_f32_16x16x32_bf16 v[100:103], v[124:127], v[96:99], v[100:103]
	s_waitcnt lgkmcnt(1)
	v_mfma_f32_16x16x32_bf16 v[104:107], v[132:135], v[96:99], v[104:107]
	s_waitcnt lgkmcnt(0)
	v_mfma_f32_16x16x32_bf16 v[94:97], v[140:143], v[96:99], v[92:95]
	s_nop 2
	v_cndmask_b32_e64 v92, v108, 0, s[28:29]
	v_cndmask_b32_e64 v93, 0, v109, s[30:31]
	v_cndmask_b32_e64 v99, v110, 0, s[34:35]
	v_cndmask_b32_e64 v108, v111, 0, s[36:37]
	v_cvt_pk_bf16_f32 v98, v92, v93
	v_cvt_pk_bf16_f32 v99, v99, v108
	v_add_u32_e32 v92, v90, v211
	ds_write_b64 v92, v[98:99]
	v_cndmask_b32_e64 v93, v100, 0, s[20:21]
	v_cndmask_b32_e64 v98, 0, v101, s[22:23]
	v_cndmask_b32_e64 v99, v102, 0, s[24:25]
	v_cndmask_b32_e64 v100, v103, 0, s[26:27]
	v_cvt_pk_bf16_f32 v98, v93, v98
	v_cvt_pk_bf16_f32 v99, v99, v100
	ds_write_b64 v88, v[98:99]
	v_cndmask_b32_e64 v93, v104, 0, s[12:13]
	v_cndmask_b32_e64 v98, 0, v105, s[14:15]
	v_cndmask_b32_e64 v99, v106, 0, s[16:17]
	v_cndmask_b32_e64 v100, v107, 0, s[18:19]
	v_cvt_pk_bf16_f32 v98, v93, v98
	v_cndmask_b32_e64 v93, v94, 0, vcc
	v_cndmask_b32_e64 v94, 0, v95, s[6:7]
	v_cndmask_b32_e64 v95, v96, 0, s[8:9]
	v_cndmask_b32_e64 v96, v97, 0, s[10:11]
	v_cvt_pk_bf16_f32 v99, v99, v100
	v_cvt_pk_bf16_f32 v94, v93, v94
	v_cvt_pk_bf16_f32 v95, v95, v96
	ds_write_b64 v87, v[98:99]
	ds_write_b64 v86, v[94:95]
	s_waitcnt lgkmcnt(0)
	s_barrier
	s_add_i32 s33, s33, -1
	s_mov_b64 s[38:39], 0x80000
	v_lshl_add_u64 v[84:85], v[84:85], 0, s[38:39]
	s_cmp_lg_u32 s33, 0
	v_lshl_add_u64 v[82:83], v[82:83], 0, s[72:73]
	s_cbranch_scc1 .LBB0_418
	s_waitcnt vmcnt(19)
	ds_write_b128 v253, v[2:5]
	s_waitcnt vmcnt(18)
	ds_write_b128 v91, v[6:9] offset:33792
	s_waitcnt vmcnt(17)
	ds_write_b128 v253, v[10:13] offset:4224
	s_waitcnt vmcnt(16)
	ds_write_b128 v246, v[14:17] offset:38144
	s_waitcnt vmcnt(15)
	ds_write_b128 v253, v[18:21] offset:8448
	s_waitcnt vmcnt(14)
	ds_write_b128 v91, v[22:25] offset:42496
	s_waitcnt vmcnt(13)
	ds_write_b128 v253, v[26:29] offset:12672
	s_waitcnt vmcnt(12)
	ds_write_b128 v246, v[30:33] offset:46848
	s_waitcnt vmcnt(11)
	ds_write_b128 v253, v[34:37] offset:16896
	s_waitcnt vmcnt(10)
	ds_write_b128 v91, v[38:41] offset:51200
	s_waitcnt vmcnt(9)
	ds_write_b128 v253, v[42:45] offset:21120
	s_waitcnt vmcnt(8)
	ds_write_b128 v246, v[46:49] offset:55552
	s_waitcnt vmcnt(7)
	ds_write_b128 v253, v[50:53] offset:25344
	s_waitcnt vmcnt(6)
	ds_write_b128 v91, v[54:57] offset:59904
	s_waitcnt vmcnt(5)
	ds_write_b128 v253, v[58:61] offset:29568
	s_waitcnt vmcnt(4)
	ds_write_b128 v246, v[62:65] offset:64256
	s_waitcnt vmcnt(3)
	ds_write_b128 v254, v[66:69]
	s_waitcnt vmcnt(2)
	ds_write_b128 v254, v[70:73] offset:4608
	s_waitcnt vmcnt(1)
	ds_write_b128 v254, v[74:77] offset:9216
	s_waitcnt vmcnt(0)
	ds_write_b128 v254, v[78:81] offset:13824
	s_waitcnt lgkmcnt(0)
	s_barrier
; #define LAS __attribute__((address_space(3)))
; __device__ __forceinline__ unsigned cvt2(float a, float b) { f32x2s v = {a, b}; bf16x2_t r = __builtin_convertvector(v, bf16x2_t); return __builtin_bit_cast(unsigned, r); }
; #define SC_BAR() do { asm volatile("s_waitcnt lgkmcnt(0)" ::: "memory"); __builtin_amdgcn_s_barrier(); asm volatile("" ::: "memory"); } while (0)
; #define LD_S(buf, ks) do { fbq[buf] = *(const LAS bf16x8s*)(lds + SC_QI + (16 * cw + fr) * SC_QS + (32 * (ks) + 8 * fq) * 2); \
;                 _Pragma("unroll") for (int tj = 0; tj < 4; ++tj) fak[buf][tj] = *(const LAS bf16x8s*)(lds + SC_KI + (16 * tj + fr) * SC_KS + (32 * (ks) + 8 * fq) * 2); } while (0)
; template <bool GLA>
; __device__ __forceinline__ void scan_item2(LAS unsigned char* lds, const bf16* Qd, const bf16* Kd, const bf16* V, bf16* O, const float* EG, int ldqk, int ldv, int b, int h, int dvs, float e_const, int tid) {
;     ...
;             f32x4 sa[4];
; #pragma unroll
;             for (int tj = 0; tj < 4; ++tj) sa[tj] = (f32x4){0.f, 0.f, 0.f, 0.f};
;             bf16x8s fbq[3], fak[3][4];
;     ...
;             LD_S(0, 0); LD_S(1, 1); LD_S(2, 2);
; #pragma unroll
;             for (int ks = 0; ks < 8; ++ks) {
;                 __builtin_amdgcn_sched_barrier(0);
; #pragma unroll
;                 for (int tj = 0; tj < 4; ++tj) sa[tj] = __builtin_amdgcn_mfma_f32_16x16x32_bf16(fak[ks % 3][tj], fbq[ks % 3], sa[tj], 0, 0, 0);
;                 __builtin_amdgcn_sched_barrier(0);
;                 if (ks + 3 < 8) LD_S(ks % 3, ks + 3);
;             }
;     ...
;             { const int i = 16 * cw + fr;
; #pragma unroll
;               for (int tj = 0; tj < 4; ++tj) { const int j0 = 16 * tj + 4 * fq;
;                   const float p0 = (j0 + 0 <= i) ? sa[tj][0] : 0.f, p1 = (j0 + 1 <= i) ? sa[tj][1] : 0.f, p2 = (j0 + 2 <= i) ? sa[tj][2] : 0.f, p3 = (j0 + 3 <= i) ? sa[tj][3] : 0.f;
;                   v2u pw; pw.x = cvt2(p0, p1); pw.y = cvt2(p2, p3);
;                   *(LAS v2u*)(lds + SC_PI + i * SC_PS + j0 * 2) = pw; } }
;             SC_BAR();
;         }
;         SC_BAR();
	ds_read_b128 v[2:5], v89
	ds_read_b128 v[6:9], v89 offset:64
	ds_read_b128 v[10:13], v1 offset:42496
	ds_read_b128 v[14:17], v1 offset:42560
	ds_read_b128 v[18:21], v1 offset:59904
	ds_read_b128 v[22:25], v1 offset:59968
	ds_read_b128 v[26:29], v1 offset:33792
	ds_read_b128 v[30:33], v89 offset:128
	ds_read_b128 v[34:37], v1 offset:33856
	ds_read_b128 v[38:41], v1 offset:33920
	ds_read_b128 v[42:45], v1 offset:51200
	ds_read_b128 v[46:49], v1 offset:42624
	ds_read_b128 v[50:53], v1 offset:51264
	ds_read_b128 v[54:57], v1 offset:51328
	ds_read_b128 v[58:61], v1 offset:60032
	s_waitcnt lgkmcnt(8)
	v_mfma_f32_16x16x32_bf16 v[26:29], v[26:29], v[2:5], 0
	v_mfma_f32_16x16x32_bf16 v[10:13], v[10:13], v[2:5], 0
	s_waitcnt lgkmcnt(4)
	v_mfma_f32_16x16x32_bf16 v[42:45], v[42:45], v[2:5], 0
	v_mfma_f32_16x16x32_bf16 v[2:5], v[18:21], v[2:5], 0
	ds_read_b128 v[18:21], v89 offset:192
	ds_read_b128 v[62:65], v1 offset:33984
	ds_read_b128 v[66:69], v1 offset:42688
	ds_read_b128 v[70:73], v1 offset:51392
	ds_read_b128 v[74:77], v1 offset:60096
	v_mfma_f32_16x16x32_bf16 v[26:29], v[34:37], v[6:9], v[26:29]
	v_mfma_f32_16x16x32_bf16 v[10:13], v[14:17], v[6:9], v[10:13]
	s_waitcnt lgkmcnt(7)
	v_mfma_f32_16x16x32_bf16 v[14:17], v[50:53], v[6:9], v[42:45]
	v_mfma_f32_16x16x32_bf16 v[2:5], v[22:25], v[6:9], v[2:5]
	ds_read_b128 v[6:9], v89 offset:256
	ds_read_b128 v[22:25], v1 offset:34048
	ds_read_b128 v[34:37], v1 offset:42752
	ds_read_b128 v[42:45], v1 offset:51456
	ds_read_b128 v[50:53], v1 offset:60160
	v_mfma_f32_16x16x32_bf16 v[26:29], v[38:41], v[30:33], v[26:29]
	v_mfma_f32_16x16x32_bf16 v[10:13], v[46:49], v[30:33], v[10:13]
	s_waitcnt lgkmcnt(11)
	v_mfma_f32_16x16x32_bf16 v[14:17], v[54:57], v[30:33], v[14:17]
	s_waitcnt lgkmcnt(10)
	v_mfma_f32_16x16x32_bf16 v[2:5], v[58:61], v[30:33], v[2:5]
	ds_read_b128 v[30:33], v89 offset:320
	ds_read_b128 v[38:41], v1 offset:34112
	ds_read_b128 v[46:49], v1 offset:42816
	ds_read_b128 v[54:57], v1 offset:51520
	ds_read_b128 v[58:61], v1 offset:60224
	s_waitcnt lgkmcnt(13)
	v_mfma_f32_16x16x32_bf16 v[26:29], v[62:65], v[18:21], v[26:29]
	s_waitcnt lgkmcnt(12)
	v_mfma_f32_16x16x32_bf16 v[10:13], v[66:69], v[18:21], v[10:13]
	s_waitcnt lgkmcnt(11)
	v_mfma_f32_16x16x32_bf16 v[14:17], v[70:73], v[18:21], v[14:17]
	s_waitcnt lgkmcnt(10)
	v_mfma_f32_16x16x32_bf16 v[2:5], v[74:77], v[18:21], v[2:5]
	ds_read_b128 v[18:21], v89 offset:384
	ds_read_b128 v[62:65], v1 offset:34176
	ds_read_b128 v[66:69], v1 offset:42880
	ds_read_b128 v[70:73], v1 offset:51584
	ds_read_b128 v[74:77], v1 offset:60288
	s_waitcnt lgkmcnt(13)
	v_mfma_f32_16x16x32_bf16 v[22:25], v[22:25], v[6:9], v[26:29]
	s_waitcnt lgkmcnt(12)
	v_mfma_f32_16x16x32_bf16 v[10:13], v[34:37], v[6:9], v[10:13]
	s_waitcnt lgkmcnt(11)
	v_mfma_f32_16x16x32_bf16 v[14:17], v[42:45], v[6:9], v[14:17]
	s_waitcnt lgkmcnt(10)
	v_mfma_f32_16x16x32_bf16 v[2:5], v[50:53], v[6:9], v[2:5]
	ds_read_b128 v[6:9], v89 offset:448
	ds_read_b128 v[26:29], v1 offset:34240
	ds_read_b128 v[34:37], v1 offset:42944
	ds_read_b128 v[42:45], v1 offset:51648
	ds_read_b128 v[50:53], v1 offset:60352
	s_waitcnt lgkmcnt(13)
	v_mfma_f32_16x16x32_bf16 v[22:25], v[38:41], v[30:33], v[22:25]
	s_waitcnt lgkmcnt(12)
	v_mfma_f32_16x16x32_bf16 v[10:13], v[46:49], v[30:33], v[10:13]
	s_waitcnt lgkmcnt(11)
	v_mfma_f32_16x16x32_bf16 v[14:17], v[54:57], v[30:33], v[14:17]
	s_waitcnt lgkmcnt(10)
	v_mfma_f32_16x16x32_bf16 v[2:5], v[58:61], v[30:33], v[2:5]
	s_waitcnt lgkmcnt(8)
	v_mfma_f32_16x16x32_bf16 v[22:25], v[62:65], v[18:21], v[22:25]
	s_waitcnt lgkmcnt(7)
	v_mfma_f32_16x16x32_bf16 v[10:13], v[66:69], v[18:21], v[10:13]
	s_waitcnt lgkmcnt(6)
	v_mfma_f32_16x16x32_bf16 v[14:17], v[70:73], v[18:21], v[14:17]
	s_waitcnt lgkmcnt(5)
	v_mfma_f32_16x16x32_bf16 v[2:5], v[74:77], v[18:21], v[2:5]
	s_waitcnt lgkmcnt(3)
	v_mfma_f32_16x16x32_bf16 v[18:21], v[26:29], v[6:9], v[22:25]
	s_waitcnt lgkmcnt(2)
	v_mfma_f32_16x16x32_bf16 v[10:13], v[34:37], v[6:9], v[10:13]
	s_waitcnt lgkmcnt(1)
	v_mfma_f32_16x16x32_bf16 v[14:17], v[42:45], v[6:9], v[14:17]
	s_waitcnt lgkmcnt(0)
	v_mfma_f32_16x16x32_bf16 v[2:5], v[50:53], v[6:9], v[2:5]
	s_nop 1
	v_cndmask_b32_e64 v6, v18, 0, s[28:29]
	v_cndmask_b32_e64 v7, 0, v19, s[30:31]
	v_cndmask_b32_e64 v8, v20, 0, s[34:35]
	v_cndmask_b32_e64 v9, v21, 0, s[36:37]
	v_cvt_pk_bf16_f32 v6, v6, v7
	v_cvt_pk_bf16_f32 v7, v8, v9
	ds_write_b64 v92, v[6:7]
	v_cndmask_b32_e64 v6, v10, 0, s[20:21]
	v_cndmask_b32_e64 v7, 0, v11, s[22:23]
	v_cndmask_b32_e64 v8, v12, 0, s[24:25]
	v_cndmask_b32_e64 v9, v13, 0, s[26:27]
	v_cvt_pk_bf16_f32 v6, v6, v7
	v_cvt_pk_bf16_f32 v7, v8, v9
	ds_write_b64 v88, v[6:7]
	v_cndmask_b32_e64 v6, v14, 0, s[12:13]
	v_cndmask_b32_e64 v7, 0, v15, s[14:15]
	v_cndmask_b32_e64 v8, v16, 0, s[16:17]
	v_cndmask_b32_e64 v9, v17, 0, s[18:19]
	v_cndmask_b32_e64 v2, v2, 0, vcc
	v_cndmask_b32_e64 v3, 0, v3, s[6:7]
	v_cndmask_b32_e64 v4, v4, 0, s[8:9]
	v_cndmask_b32_e64 v5, v5, 0, s[10:11]
	v_cvt_pk_bf16_f32 v6, v6, v7
	v_cvt_pk_bf16_f32 v7, v8, v9
	v_cvt_pk_bf16_f32 v2, v2, v3
	v_cvt_pk_bf16_f32 v3, v4, v5
	ds_write_b64 v87, v[6:7]
	ds_write_b64 v86, v[2:3]
	s_waitcnt lgkmcnt(0)
	s_barrier
	s_waitcnt lgkmcnt(0)
	s_barrier
	s_branch .LBB0_411
